# v60 + dense-GQA attention steps: K-fragment LDS reads issued earlier into spare VGPRs with counted lgkmcnt waits before each MFMA
# baseline (speedup 1.0000x reference)
.LBB0_399:
	s_setprio 3
	s_mov_b32 s30, s27
	s_mov_b32 s27, s72
	s_add_i32 s53, s30, 0
	v_add_u32_e32 v0, s53, v126
	ds_read_b128 v[34:37], v0
	ds_read_b128 v[38:41], v0 offset:2048
	ds_read_b128 v[240:243], v0 offset:4096
	ds_read_b128 v[244:247], v0 offset:6144
	ds_read_b128 v[248:251], v0 offset:512
	ds_read_b128 v[252:255], v0 offset:2560
	s_add_i32 s34, s56, 0xfffc0000
	s_add_i32 s100, s55, -1
	s_and_b32 s34, s34, 0xf00000
	s_and_b32 s100, s100, 3
	s_lshl_b32 s78, s34, 1
	s_add_i32 s54, s29, 0
	s_mul_i32 s58, s100, 0x38000
	s_mov_b32 s59, s79
	s_add_u32 s98, s78, s58
	s_addc_u32 s99, s79, s79
	s_add_i32 s34, s54, s5
	v_lshl_add_u64 v[238:239], v[116:117], 0, s[98:99]
	s_mov_b32 m0, s34
	s_add_i32 s35, s34, 0x2000
	global_load_lds_dwordx4 v[238:239], off
	v_lshl_add_u64 v[238:239], v[118:119], 0, s[98:99]
	s_mov_b32 m0, s35
	s_nop 0
	global_load_lds_dwordx4 v[238:239], off
	v_exp_f32_e32 v145, v66
	v_exp_f32_e32 v146, v67
	v_exp_f32_e32 v147, v68
	v_exp_f32_e32 v148, v69
	v_exp_f32_e32 v149, v70
	v_exp_f32_e32 v150, v71
	v_exp_f32_e32 v151, v72
	s_waitcnt lgkmcnt(5)
	v_mfma_f32_32x32x16_bf16 v[82:97], v[34:37], v[110:113], v[50:65]
	v_exp_f32_e32 v152, v73
	v_exp_f32_e32 v153, v74
	v_exp_f32_e32 v154, v75
	v_exp_f32_e32 v155, v76
	v_exp_f32_e32 v156, v77
	v_exp_f32_e32 v157, v78
	s_waitcnt lgkmcnt(4)
	v_mfma_f32_32x32x16_bf16 v[82:97], v[38:41], v[106:109], v[82:97]
	v_exp_f32_e32 v158, v79
	v_exp_f32_e32 v159, v80
	v_exp_f32_e32 v160, v81
	s_waitcnt lgkmcnt(3)
	v_mfma_f32_32x32x16_bf16 v[82:97], v[240:243], v[102:105], v[82:97]
	v_add_f32_e32 v34, v129, v131
	v_add_f32_e32 v66, v132, v34
	ds_read_b128 v[46:49], v0 offset:4608
	s_waitcnt lgkmcnt(3)
	v_mfma_f32_32x32x16_bf16 v[82:97], v[244:247], v[98:101], v[82:97]
	ds_read_b128 v[38:41], v0 offset:6656
	v_add_f32_e32 v0, v135, v66
	v_add_f32_e32 v0, v136, v0
	v_add_f32_e32 v0, v139, v0
	v_add_f32_e32 v0, v140, v0
	v_add_f32_e32 v0, v143, v0
	v_add_f32_e32 v0, v130, v0
	s_waitcnt lgkmcnt(2)
	v_mfma_f32_32x32x16_bf16 v[66:81], v[248:251], v[110:113], v[50:65]
	v_add_f32_e32 v0, v133, v0
	v_add_f32_e32 v0, v134, v0
	v_add_f32_e32 v0, v137, v0
	v_add_f32_e32 v0, v138, v0
	s_setprio 2
	v_add_f32_e32 v0, v141, v0
	v_add_f32_e32 v0, v142, v0
	v_add_f32_e32 v0, v144, v0
	v_mfma_f32_32x32x16_bf16 v[66:81], v[252:255], v[106:109], v[66:81]
	v_add_f32_e32 v0, v145, v0
	v_add_f32_e32 v0, v146, v0
	v_add_f32_e32 v0, v147, v0
	v_add_f32_e32 v0, v148, v0
	v_add_f32_e32 v0, v149, v0
	v_add_f32_e32 v0, v150, v0
	v_add_f32_e32 v0, v151, v0
	s_waitcnt lgkmcnt(1)
	v_mfma_f32_32x32x16_bf16 v[66:81], v[46:49], v[102:105], v[66:81]
	v_add_f32_e32 v0, v152, v0
	v_add_f32_e32 v0, v153, v0
	v_add_f32_e32 v0, v154, v0
	v_add_f32_e32 v0, v155, v0
	v_add_f32_e32 v0, v156, v0
	v_add_f32_e32 v0, v157, v0
	v_add_f32_e32 v0, v158, v0
	s_waitcnt lgkmcnt(0)
	v_mfma_f32_32x32x16_bf16 v[66:81], v[38:41], v[98:101], v[66:81]
	v_cvt_pk_bf16_f32 v34, v129, v131
	v_add_f32_e32 v161, v159, v0
	v_cvt_pk_bf16_f32 v35, v132, v135
	v_cvt_pk_bf16_f32 v36, v136, v139
	v_cvt_pk_bf16_f32 v37, v140, v143
	v_cvt_pk_bf16_f32 v38, v130, v133
	v_cvt_pk_bf16_f32 v39, v134, v137
	v_cvt_pk_bf16_f32 v40, v138, v141
	v_cvt_pk_bf16_f32 v41, v142, v144
	v_cvt_pk_bf16_f32 v42, v145, v146
	v_cvt_pk_bf16_f32 v43, v147, v148
	v_cvt_pk_bf16_f32 v44, v149, v150
	v_cvt_pk_bf16_f32 v45, v151, v152
	v_cvt_pk_bf16_f32 v46, v153, v154
	v_cvt_pk_bf16_f32 v47, v155, v156
	v_cvt_pk_bf16_f32 v48, v157, v158
	v_cvt_pk_bf16_f32 v49, v159, v160
	s_add_i32 s57, s72, 0
	v_add_u32_e32 v0, s57, v125
	ds_read_b64_tr_b16 v[130:131], v0 offset:8192
	ds_read_b64_tr_b16 v[132:133], v0 offset:8704
	ds_read_b64_tr_b16 v[134:135], v0 offset:12288
	v_max_f32_e32 v129, v67, v67
	s_waitcnt lgkmcnt(1)
	v_mfma_f32_32x32x16_bf16 v[18:33], v[130:133], v[34:37], v[18:33]
	ds_read_b64_tr_b16 v[136:137], v0 offset:12800
	ds_read_b64_tr_b16 v[130:131], v0 offset:9216
	s_waitcnt lgkmcnt(1)
	v_mfma_f32_32x32x16_bf16 v[2:17], v[134:137], v[34:37], v[2:17]
	ds_read_b64_tr_b16 v[132:133], v0 offset:9728
	ds_read_b64_tr_b16 v[34:35], v0 offset:13312
	s_waitcnt lgkmcnt(1)
	v_mfma_f32_32x32x16_bf16 v[18:33], v[130:133], v[38:41], v[18:33]
	ds_read_b64_tr_b16 v[36:37], v0 offset:13824
	ds_read_b64_tr_b16 v[130:131], v0 offset:10240
	s_waitcnt lgkmcnt(1)
	v_mfma_f32_32x32x16_bf16 v[2:17], v[34:37], v[38:41], v[2:17]
	ds_read_b64_tr_b16 v[132:133], v0 offset:10752
	ds_read_b64_tr_b16 v[34:35], v0 offset:11264
	ds_read_b64_tr_b16 v[36:37], v0 offset:11776
	ds_read_b64_tr_b16 v[38:39], v0 offset:14336
	ds_read_b64_tr_b16 v[40:41], v0 offset:14848
	ds_read_b64_tr_b16 v[134:135], v0 offset:15360
	ds_read_b64_tr_b16 v[136:137], v0 offset:15872
	s_waitcnt lgkmcnt(6)
	v_mfma_f32_32x32x16_bf16 v[18:33], v[130:133], v[42:45], v[18:33]
	v_max_f32_e32 v130, v83, v83
	v_max_f32_e32 v129, v130, v129
	v_max3_f32 v130, v82, v66, v84
	s_setprio 1
	v_max3_f32 v129, v129, v85, v69
	v_max3_f32 v130, v130, v68, v86
	v_max3_f32 v129, v129, v87, v71
	s_waitcnt lgkmcnt(2)
	v_mfma_f32_32x32x16_bf16 v[2:17], v[38:41], v[42:45], v[2:17]
	v_max3_f32 v38, v130, v70, v88
	v_max3_f32 v39, v129, v89, v73
	v_max3_f32 v38, v38, v72, v90
	v_max3_f32 v39, v39, v91, v75
	v_max3_f32 v38, v38, v74, v92
	v_max3_f32 v39, v39, v93, v77
	v_max3_f32 v38, v38, v76, v94
	v_mfma_f32_32x32x16_bf16 v[18:33], v[34:37], v[46:49], v[18:33]
	v_max3_f32 v34, v39, v95, v79
	v_max3_f32 v35, v38, v78, v96
	v_max3_f32 v34, v34, v97, v81
	v_add_f32_e32 v36, v160, v161
	v_max3_f32 v34, v35, v80, v34
	v_add_f32_e32 v128, v128, v36
	v_cmp_lt_f32_e32 vcc, s33, v34
	s_waitcnt lgkmcnt(0)
	v_mfma_f32_32x32x16_bf16 v[2:17], v[134:137], v[46:49], v[2:17]
	s_cbranch_vccz .LBB0_401
	v_mov_b32_e32 v35, v34
	s_nop 1
	v_permlane32_swap_b32 v34, v35
	s_nop 1
	s_nop 0
	v_max3_f32 v36, v34, v35, 0
	v_exp_f32_e64 v38, -v36
	v_add_f32_e32 v127, v127, v36
	v_xor_b32_e32 v34, 0x80000000, v127
	v_pk_add_f32 v[82:83], v[82:83], v[36:37] op_sel_hi:[1,0] neg_lo:[0,1] neg_hi:[0,1]
	v_pk_add_f32 v[66:67], v[66:67], v[36:37] op_sel_hi:[1,0] neg_lo:[0,1] neg_hi:[0,1]
	v_pk_add_f32 v[84:85], v[84:85], v[36:37] op_sel_hi:[1,0] neg_lo:[0,1] neg_hi:[0,1]
	v_pk_add_f32 v[68:69], v[68:69], v[36:37] op_sel_hi:[1,0] neg_lo:[0,1] neg_hi:[0,1]
	v_pk_add_f32 v[86:87], v[86:87], v[36:37] op_sel_hi:[1,0] neg_lo:[0,1] neg_hi:[0,1]
	v_pk_add_f32 v[70:71], v[70:71], v[36:37] op_sel_hi:[1,0] neg_lo:[0,1] neg_hi:[0,1]
	v_pk_add_f32 v[88:89], v[88:89], v[36:37] op_sel_hi:[1,0] neg_lo:[0,1] neg_hi:[0,1]
	v_pk_add_f32 v[72:73], v[72:73], v[36:37] op_sel_hi:[1,0] neg_lo:[0,1] neg_hi:[0,1]
	v_pk_add_f32 v[90:91], v[90:91], v[36:37] op_sel_hi:[1,0] neg_lo:[0,1] neg_hi:[0,1]
	v_pk_add_f32 v[74:75], v[74:75], v[36:37] op_sel_hi:[1,0] neg_lo:[0,1] neg_hi:[0,1]
	v_pk_add_f32 v[92:93], v[92:93], v[36:37] op_sel_hi:[1,0] neg_lo:[0,1] neg_hi:[0,1]
	v_pk_add_f32 v[76:77], v[76:77], v[36:37] op_sel_hi:[1,0] neg_lo:[0,1] neg_hi:[0,1]
	v_pk_add_f32 v[94:95], v[94:95], v[36:37] op_sel_hi:[1,0] neg_lo:[0,1] neg_hi:[0,1]
	v_pk_add_f32 v[78:79], v[78:79], v[36:37] op_sel_hi:[1,0] neg_lo:[0,1] neg_hi:[0,1]
	v_pk_add_f32 v[96:97], v[96:97], v[36:37] op_sel_hi:[1,0] neg_lo:[0,1] neg_hi:[0,1]
	v_pk_add_f32 v[80:81], v[80:81], v[36:37] op_sel_hi:[1,0] neg_lo:[0,1] neg_hi:[0,1]
	v_pk_mul_f32 v[32:33], v[32:33], v[38:39] op_sel_hi:[1,0]
	v_pk_mul_f32 v[30:31], v[30:31], v[38:39] op_sel_hi:[1,0]
	v_pk_mul_f32 v[28:29], v[28:29], v[38:39] op_sel_hi:[1,0]
	v_pk_mul_f32 v[26:27], v[26:27], v[38:39] op_sel_hi:[1,0]
	v_pk_mul_f32 v[24:25], v[24:25], v[38:39] op_sel_hi:[1,0]
	v_pk_mul_f32 v[22:23], v[22:23], v[38:39] op_sel_hi:[1,0]
	v_pk_mul_f32 v[20:21], v[20:21], v[38:39] op_sel_hi:[1,0]
	v_pk_mul_f32 v[18:19], v[18:19], v[38:39] op_sel_hi:[1,0]
	v_pk_mul_f32 v[16:17], v[16:17], v[38:39] op_sel_hi:[1,0]
	v_pk_mul_f32 v[14:15], v[14:15], v[38:39] op_sel_hi:[1,0]
	v_pk_mul_f32 v[12:13], v[12:13], v[38:39] op_sel_hi:[1,0]
	v_pk_mul_f32 v[10:11], v[10:11], v[38:39] op_sel_hi:[1,0]
	v_pk_mul_f32 v[8:9], v[8:9], v[38:39] op_sel_hi:[1,0]
	v_pk_mul_f32 v[6:7], v[6:7], v[38:39] op_sel_hi:[1,0]
	v_pk_mul_f32 v[4:5], v[4:5], v[38:39] op_sel_hi:[1,0]
	v_pk_mul_f32 v[2:3], v[2:3], v[38:39] op_sel_hi:[1,0]
	v_mul_f32_e32 v128, v128, v38
	v_mov_b32_e32 v35, v34
	v_mov_b32_e32 v36, v34
	v_mov_b32_e32 v37, v34
	v_mov_b32_e32 v38, v34
	v_mov_b32_e32 v39, v34
	v_mov_b32_e32 v40, v34
	v_mov_b32_e32 v41, v34
	v_mov_b32_e32 v42, v34
	v_mov_b32_e32 v43, v34
	v_mov_b32_e32 v44, v34
	v_mov_b32_e32 v45, v34
	v_mov_b32_e32 v46, v34
	v_mov_b32_e32 v47, v34
	v_mov_b32_e32 v48, v34
	v_mov_b32_e32 v49, v34
	v_mov_b32_e32 v50, v34
	v_mov_b32_e32 v51, v34
	v_mov_b32_e32 v52, v34
	v_mov_b32_e32 v53, v34
	v_mov_b32_e32 v54, v34
	v_mov_b32_e32 v55, v34
	v_mov_b32_e32 v56, v34
	v_mov_b32_e32 v57, v34
	v_mov_b32_e32 v58, v34
	v_mov_b32_e32 v59, v34
	v_mov_b32_e32 v60, v34
	v_mov_b32_e32 v61, v34
	v_mov_b32_e32 v62, v34
	v_mov_b32_e32 v63, v34
	v_mov_b32_e32 v64, v34
	v_mov_b32_e32 v65, v34
	s_branch .LBB0_402
.LBB0_401:
.LBB0_402:
	v_exp_f32_e32 v129, v82
	s_setprio 0
	v_exp_f32_e32 v146, v83
	v_exp_f32_e32 v147, v84
	v_exp_f32_e32 v148, v85
	v_exp_f32_e32 v149, v86
	v_exp_f32_e32 v150, v87
	v_exp_f32_e32 v151, v88
	v_exp_f32_e32 v152, v89
	v_exp_f32_e32 v153, v90
	v_exp_f32_e32 v154, v91
	v_exp_f32_e32 v155, v92
	v_exp_f32_e32 v156, v93
	v_exp_f32_e32 v157, v94
	v_exp_f32_e32 v158, v95
	v_exp_f32_e32 v159, v96
	v_exp_f32_e32 v160, v97
	s_add_i32 s58, s55, 4
	s_and_b32 s59, s56, 0xf00000
	s_and_b32 s58, s58, 3
	s_lshl_b32 s78, s59, 1
	s_mul_i32 s58, s58, 0x38000
	s_mov_b32 s59, s79
	s_add_u32 s98, s78, s58
	s_addc_u32 s99, s79, s79
	s_add_i32 s60, s57, s5
	v_lshl_add_u64 v[82:83], v[116:117], 0, s[98:99]
	s_mov_b32 m0, s60
	s_waitcnt vmcnt(0)
	s_barrier
	s_setprio 3
	v_add_u32_e32 v142, s54, v126
	ds_read_b128 v[130:133], v142
	ds_read_b128 v[134:137], v142 offset:2048
	ds_read_b128 v[240:243], v142 offset:6144
	global_load_lds_dwordx4 v[82:83], off
	v_lshl_add_u64 v[82:83], v[118:119], 0, s[98:99]
	s_add_i32 m0, s60, 0x2000
	s_nop 0
	global_load_lds_dwordx4 v[82:83], off
	v_exp_f32_e32 v161, v66
	v_exp_f32_e32 v162, v67
	v_exp_f32_e32 v163, v68
	v_exp_f32_e32 v164, v69
	ds_read_b128 v[66:69], v142 offset:4096
	v_exp_f32_e32 v165, v70
	v_exp_f32_e32 v166, v71
	s_waitcnt lgkmcnt(3)
	v_mfma_f32_32x32x16_bf16 v[82:97], v[130:133], v[110:113], v[50:65]
	v_exp_f32_e32 v167, v72
	v_exp_f32_e32 v168, v73
	v_exp_f32_e32 v169, v74
	v_exp_f32_e32 v170, v75
	v_exp_f32_e32 v171, v76
	v_exp_f32_e32 v172, v77
	s_waitcnt lgkmcnt(2)
	v_mfma_f32_32x32x16_bf16 v[82:97], v[134:137], v[106:109], v[82:97]
	ds_read_b128 v[130:133], v142 offset:512
	ds_read_b128 v[134:137], v142 offset:2560
	ds_read_b128 v[138:141], v142 offset:4608
	ds_read_b128 v[142:145], v142 offset:6656
	v_exp_f32_e32 v173, v78
	v_exp_f32_e32 v174, v79
	v_exp_f32_e32 v175, v80
	v_exp_f32_e32 v176, v81
	s_waitcnt lgkmcnt(4)
	v_mfma_f32_32x32x16_bf16 v[82:97], v[66:69], v[102:105], v[82:97]
	v_add_f32_e32 v66, v129, v146
	v_add_f32_e32 v66, v147, v66
	v_add_f32_e32 v66, v148, v66
	v_add_f32_e32 v66, v149, v66
	v_add_f32_e32 v66, v150, v66
	v_add_f32_e32 v66, v151, v66
	v_add_f32_e32 v66, v152, v66
	v_add_f32_e32 v66, v153, v66
	s_waitcnt lgkmcnt(3)
	v_mfma_f32_32x32x16_bf16 v[82:97], v[240:243], v[98:101], v[82:97]
	v_add_f32_e32 v177, v154, v66
	v_mfma_f32_32x32x16_bf16 v[66:81], v[130:133], v[110:113], v[50:65]
	v_add_f32_e32 v130, v155, v177
	v_add_f32_e32 v130, v156, v130
	v_add_f32_e32 v130, v157, v130
	v_add_f32_e32 v130, v158, v130
	v_add_f32_e32 v130, v159, v130
	v_add_f32_e32 v130, v160, v130
	v_add_f32_e32 v130, v161, v130
	s_waitcnt lgkmcnt(2)
	v_mfma_f32_32x32x16_bf16 v[66:81], v[134:137], v[106:109], v[66:81]
	v_add_f32_e32 v130, v162, v130
	v_add_f32_e32 v130, v163, v130
	v_add_f32_e32 v130, v164, v130
	v_add_f32_e32 v130, v165, v130
	v_add_f32_e32 v130, v166, v130
	v_add_f32_e32 v130, v167, v130
	s_setprio 2
	v_add_f32_e32 v130, v168, v130
	s_waitcnt lgkmcnt(1)
	v_mfma_f32_32x32x16_bf16 v[66:81], v[138:141], v[102:105], v[66:81]
	v_add_f32_e32 v130, v169, v130
	v_add_f32_e32 v130, v170, v130
	v_add_f32_e32 v130, v171, v130
	v_add_f32_e32 v130, v172, v130
	v_add_f32_e32 v130, v173, v130
	v_add_f32_e32 v130, v174, v130
	v_add_f32_e32 v177, v175, v130
	s_waitcnt lgkmcnt(0)
	v_mfma_f32_32x32x16_bf16 v[66:81], v[142:145], v[98:101], v[66:81]
	v_cvt_pk_bf16_f32 v130, v129, v146
	v_cvt_pk_bf16_f32 v131, v147, v148
	v_cvt_pk_bf16_f32 v132, v149, v150
	v_cvt_pk_bf16_f32 v133, v151, v152
	v_cvt_pk_bf16_f32 v134, v153, v154
	v_cvt_pk_bf16_f32 v135, v155, v156
	v_cvt_pk_bf16_f32 v136, v157, v158
	v_cvt_pk_bf16_f32 v137, v159, v160
	v_cvt_pk_bf16_f32 v138, v161, v162
	v_cvt_pk_bf16_f32 v139, v163, v164
	v_cvt_pk_bf16_f32 v140, v165, v166
	v_cvt_pk_bf16_f32 v141, v167, v168
	v_cvt_pk_bf16_f32 v142, v169, v170
	v_cvt_pk_bf16_f32 v143, v171, v172
	v_cvt_pk_bf16_f32 v144, v173, v174
	v_cvt_pk_bf16_f32 v145, v175, v176
	v_add_u32_e32 v129, s53, v125
	ds_read_b64_tr_b16 v[146:147], v129 offset:8192
	ds_read_b64_tr_b16 v[148:149], v129 offset:8704
	ds_read_b64_tr_b16 v[150:151], v129 offset:12288
	s_waitcnt lgkmcnt(1)
	v_mfma_f32_32x32x16_bf16 v[18:33], v[146:149], v[130:133], v[18:33]
	ds_read_b64_tr_b16 v[152:153], v129 offset:12800
	ds_read_b64_tr_b16 v[146:147], v129 offset:9216
	s_waitcnt lgkmcnt(1)
	v_mfma_f32_32x32x16_bf16 v[2:17], v[150:153], v[130:133], v[2:17]
	ds_read_b64_tr_b16 v[148:149], v129 offset:9728
	ds_read_b64_tr_b16 v[130:131], v129 offset:13312
	s_waitcnt lgkmcnt(1)
	v_mfma_f32_32x32x16_bf16 v[18:33], v[146:149], v[134:137], v[18:33]
	ds_read_b64_tr_b16 v[132:133], v129 offset:13824
	ds_read_b64_tr_b16 v[146:147], v129 offset:10240
	s_waitcnt lgkmcnt(1)
	v_mfma_f32_32x32x16_bf16 v[2:17], v[130:133], v[134:137], v[2:17]
	ds_read_b64_tr_b16 v[148:149], v129 offset:10752
	ds_read_b64_tr_b16 v[130:131], v129 offset:11264
	ds_read_b64_tr_b16 v[132:133], v129 offset:11776
	ds_read_b64_tr_b16 v[134:135], v129 offset:14336
	ds_read_b64_tr_b16 v[136:137], v129 offset:14848
	ds_read_b64_tr_b16 v[150:151], v129 offset:15360
	ds_read_b64_tr_b16 v[152:153], v129 offset:15872
	v_max_f32_e32 v129, v67, v67
	s_waitcnt lgkmcnt(6)
	v_mfma_f32_32x32x16_bf16 v[18:33], v[146:149], v[138:141], v[18:33]
	v_max_f32_e32 v146, v83, v83
	v_max_f32_e32 v129, v146, v129
	v_max3_f32 v146, v82, v66, v84
	v_max3_f32 v129, v129, v85, v69
	v_max3_f32 v146, v146, v68, v86
	v_max3_f32 v129, v129, v87, v71
	v_max3_f32 v129, v129, v89, v73
	s_waitcnt lgkmcnt(2)
	s_setprio 1
	v_mfma_f32_32x32x16_bf16 v[2:17], v[134:137], v[138:141], v[2:17]
	v_max3_f32 v134, v146, v70, v88
	v_max3_f32 v134, v134, v72, v90
	v_max3_f32 v129, v129, v91, v75
	v_max3_f32 v134, v134, v74, v92
	v_max3_f32 v129, v129, v93, v77
	v_max3_f32 v134, v134, v76, v94
	v_max3_f32 v129, v129, v95, v79
	v_mfma_f32_32x32x16_bf16 v[18:33], v[130:133], v[142:145], v[18:33]
	v_max3_f32 v130, v134, v78, v96
	v_max3_f32 v129, v129, v97, v81
	v_add_f32_e32 v131, v176, v177
	v_max3_f32 v129, v130, v80, v129
	v_add_f32_e32 v128, v128, v131
	v_cmp_lt_f32_e32 vcc, s33, v129
	s_waitcnt lgkmcnt(0)
	v_mfma_f32_32x32x16_bf16 v[2:17], v[150:153], v[142:145], v[2:17]
	s_cbranch_vccz .LBB0_404
	v_mov_b32_e32 v34, v129
	s_nop 1
	v_permlane32_swap_b32 v129, v34
	s_nop 1
	s_nop 0
	v_max3_f32 v36, v129, v34, 0
	v_exp_f32_e64 v38, -v36
	v_add_f32_e32 v127, v127, v36
	v_xor_b32_e32 v34, 0x80000000, v127
	v_pk_add_f32 v[82:83], v[82:83], v[36:37] op_sel_hi:[1,0] neg_lo:[0,1] neg_hi:[0,1]
	v_pk_add_f32 v[84:85], v[84:85], v[36:37] op_sel_hi:[1,0] neg_lo:[0,1] neg_hi:[0,1]
	v_pk_add_f32 v[86:87], v[86:87], v[36:37] op_sel_hi:[1,0] neg_lo:[0,1] neg_hi:[0,1]
	v_pk_add_f32 v[88:89], v[88:89], v[36:37] op_sel_hi:[1,0] neg_lo:[0,1] neg_hi:[0,1]
	v_pk_add_f32 v[90:91], v[90:91], v[36:37] op_sel_hi:[1,0] neg_lo:[0,1] neg_hi:[0,1]
	v_pk_add_f32 v[92:93], v[92:93], v[36:37] op_sel_hi:[1,0] neg_lo:[0,1] neg_hi:[0,1]
	v_pk_add_f32 v[94:95], v[94:95], v[36:37] op_sel_hi:[1,0] neg_lo:[0,1] neg_hi:[0,1]
	v_pk_add_f32 v[96:97], v[96:97], v[36:37] op_sel_hi:[1,0] neg_lo:[0,1] neg_hi:[0,1]
	v_sub_f32_e32 v81, v81, v36
	v_sub_f32_e32 v80, v80, v36
	v_sub_f32_e32 v79, v79, v36
	v_sub_f32_e32 v78, v78, v36
	v_sub_f32_e32 v77, v77, v36
	v_sub_f32_e32 v76, v76, v36
	v_sub_f32_e32 v75, v75, v36
	v_sub_f32_e32 v74, v74, v36
	v_sub_f32_e32 v73, v73, v36
	v_sub_f32_e32 v72, v72, v36
	v_sub_f32_e32 v71, v71, v36
	v_sub_f32_e32 v70, v70, v36
	v_sub_f32_e32 v69, v69, v36
	v_sub_f32_e32 v68, v68, v36
	v_sub_f32_e32 v67, v67, v36
	v_sub_f32_e32 v66, v66, v36
	v_pk_mul_f32 v[32:33], v[32:33], v[38:39] op_sel_hi:[1,0]
	v_pk_mul_f32 v[30:31], v[30:31], v[38:39] op_sel_hi:[1,0]
	v_pk_mul_f32 v[28:29], v[28:29], v[38:39] op_sel_hi:[1,0]
	v_pk_mul_f32 v[26:27], v[26:27], v[38:39] op_sel_hi:[1,0]
	v_pk_mul_f32 v[24:25], v[24:25], v[38:39] op_sel_hi:[1,0]
	v_pk_mul_f32 v[22:23], v[22:23], v[38:39] op_sel_hi:[1,0]
	v_pk_mul_f32 v[20:21], v[20:21], v[38:39] op_sel_hi:[1,0]
	v_pk_mul_f32 v[18:19], v[18:19], v[38:39] op_sel_hi:[1,0]
	v_pk_mul_f32 v[16:17], v[16:17], v[38:39] op_sel_hi:[1,0]
	v_pk_mul_f32 v[14:15], v[14:15], v[38:39] op_sel_hi:[1,0]
	v_pk_mul_f32 v[12:13], v[12:13], v[38:39] op_sel_hi:[1,0]
	v_pk_mul_f32 v[10:11], v[10:11], v[38:39] op_sel_hi:[1,0]
	v_pk_mul_f32 v[8:9], v[8:9], v[38:39] op_sel_hi:[1,0]
	v_pk_mul_f32 v[6:7], v[6:7], v[38:39] op_sel_hi:[1,0]
	v_pk_mul_f32 v[4:5], v[4:5], v[38:39] op_sel_hi:[1,0]
	v_pk_mul_f32 v[2:3], v[2:3], v[38:39] op_sel_hi:[1,0]
	v_mul_f32_e32 v128, v128, v38
	v_mov_b32_e32 v35, v34
	v_mov_b32_e32 v36, v34
	v_mov_b32_e32 v37, v34
	v_mov_b32_e32 v38, v34
	v_mov_b32_e32 v39, v34
	v_mov_b32_e32 v40, v34
	v_mov_b32_e32 v41, v34
	v_mov_b32_e32 v42, v34
	v_mov_b32_e32 v43, v34
	v_mov_b32_e32 v44, v34
	v_mov_b32_e32 v45, v34
	v_mov_b32_e32 v46, v34
	v_mov_b32_e32 v47, v34
	v_mov_b32_e32 v48, v34
	v_mov_b32_e32 v49, v34
	v_mov_b32_e32 v50, v34
	v_mov_b32_e32 v51, v34
	v_mov_b32_e32 v52, v34
	v_mov_b32_e32 v53, v34
	v_mov_b32_e32 v54, v34
	v_mov_b32_e32 v55, v34
	v_mov_b32_e32 v56, v34
	v_mov_b32_e32 v57, v34
	v_mov_b32_e32 v58, v34
	v_mov_b32_e32 v59, v34
	v_mov_b32_e32 v60, v34
	v_mov_b32_e32 v61, v34
	v_mov_b32_e32 v62, v34
	v_mov_b32_e32 v63, v34
	v_mov_b32_e32 v64, v34
	v_mov_b32_e32 v65, v34
